# plus: HN (P6) and H2B (P9) tiles stored write-through (sc1): less dirty L2 data for the barrier's writeback
# speedup vs baseline: 1.0058x; 1.0058x over previous
.LBB0_754:
	s_or_b64 exec, exec, s[12:13]
	v_mov_b32_e32 v128, s22
	v_mov_b32_e32 v129, s23
	s_waitcnt lgkmcnt(0)
	s_barrier
	v_lshl_add_u64 v[152:153], v[200:201], 2, v[128:129]
	global_load_dwordx4 v[132:135], v[152:153], off
	global_load_dwordx4 v[128:131], v[152:153], off offset:16
	ds_read_b32 v158, v209 offset:8192
	v_lshlrev_b64 v[144:145], 10, v[144:145]
	s_add_u32 s8, s18, 0x29d00000
	v_lshl_add_u64 v[160:161], v[144:145], 0, v[200:201]
	s_addc_u32 s9, s19, 0
	v_cvt_pk_bf16_f32 v154, v112, v113
	v_cvt_pk_bf16_f32 v155, v114, v115
	v_cvt_pk_bf16_f32 v156, v116, v117
	v_lshlrev_b64 v[160:161], 1, v[160:161]
	s_waitcnt lgkmcnt(0)
	v_pk_mul_f32 v[114:115], v[114:115], v[158:159] op_sel_hi:[1,0]
	v_pk_mul_f32 v[112:113], v[112:113], v[158:159] op_sel_hi:[1,0]
	v_pk_mul_f32 v[116:117], v[116:117], v[158:159] op_sel_hi:[1,0]
	v_cvt_pk_bf16_f32 v157, v118, v119
	v_lshl_add_u64 v[168:169], s[8:9], 0, v[160:161]
	v_pk_mul_f32 v[118:119], v[118:119], v[158:159] op_sel_hi:[1,0]
	global_store_dwordx4 v[168:169], v[154:157], off nt
	v_lshlrev_b64 v[150:151], 10, v[150:151]
	s_add_u32 s10, s18, 0x12300000
	v_lshl_add_u64 v[162:163], v[150:151], 0, v[200:201]
	s_addc_u32 s11, s19, 0
	v_lshlrev_b64 v[162:163], 1, v[162:163]
	v_lshl_add_u64 v[154:155], s[10:11], 0, v[160:161]
	v_lshl_add_u64 v[170:171], s[8:9], 0, v[162:163]
	v_lshlrev_b64 v[148:149], 10, v[148:149]
	v_lshl_add_u64 v[164:165], v[148:149], 0, v[200:201]
	v_lshl_add_u64 v[156:157], s[10:11], 0, v[162:163]
	v_lshlrev_b64 v[164:165], 1, v[164:165]
	v_lshl_add_u64 v[172:173], s[8:9], 0, v[164:165]
	v_lshlrev_b64 v[146:147], 10, v[146:147]
	v_lshl_add_u64 v[166:167], v[146:147], 0, v[200:201]
	v_lshlrev_b64 v[166:167], 1, v[166:167]
	v_lshl_add_u64 v[160:161], s[10:11], 0, v[164:165]
	v_lshl_add_u64 v[174:175], s[8:9], 0, v[166:167]
	s_waitcnt vmcnt(2)
	v_pk_mul_f32 v[114:115], v[134:135], v[114:115]
	v_pk_mul_f32 v[112:113], v[132:133], v[112:113]
	s_waitcnt vmcnt(1)
	v_pk_mul_f32 v[116:117], v[128:129], v[116:117]
	v_pk_mul_f32 v[118:119], v[130:131], v[118:119]
	v_cvt_pk_bf16_f32 v112, v112, v113
	v_cvt_pk_bf16_f32 v113, v114, v115
	v_cvt_pk_bf16_f32 v114, v116, v117
	s_nop 0
	v_cvt_pk_bf16_f32 v115, v118, v119
	ds_read_b32 v116, v209 offset:8256
	global_store_dwordx4 v[154:155], v[112:115], off sc1
	s_waitcnt lgkmcnt(0)
	v_pk_mul_f32 v[118:119], v[126:127], v[116:117] op_sel_hi:[1,0]
	v_cvt_pk_bf16_f32 v112, v120, v121
	v_cvt_pk_bf16_f32 v113, v122, v123
	v_cvt_pk_bf16_f32 v114, v124, v125
	v_cvt_pk_bf16_f32 v115, v126, v127
	global_store_dwordx4 v[170:171], v[112:115], off nt
	v_pk_mul_f32 v[118:119], v[130:131], v[118:119]
	s_nop 0
	v_pk_mul_f32 v[112:113], v[122:123], v[116:117] op_sel_hi:[1,0]
	v_pk_mul_f32 v[114:115], v[120:121], v[116:117] op_sel_hi:[1,0]
	v_pk_mul_f32 v[116:117], v[124:125], v[116:117] op_sel_hi:[1,0]
	v_pk_mul_f32 v[120:121], v[134:135], v[112:113]
	v_pk_mul_f32 v[112:113], v[132:133], v[114:115]
	v_pk_mul_f32 v[114:115], v[128:129], v[116:117]
	v_cvt_pk_bf16_f32 v112, v112, v113
	v_cvt_pk_bf16_f32 v113, v120, v121
	s_nop 0
	v_cvt_pk_bf16_f32 v114, v114, v115
	v_cvt_pk_bf16_f32 v115, v118, v119
	ds_read_b32 v116, v209 offset:8320
	global_store_dwordx4 v[156:157], v[112:115], off sc1
	s_nop 1
	v_cvt_pk_bf16_f32 v112, v104, v105
	v_cvt_pk_bf16_f32 v113, v106, v107
	v_cvt_pk_bf16_f32 v114, v108, v109
	s_waitcnt lgkmcnt(0)
	v_pk_mul_f32 v[106:107], v[106:107], v[116:117] op_sel_hi:[1,0]
	v_pk_mul_f32 v[104:105], v[104:105], v[116:117] op_sel_hi:[1,0]
	v_pk_mul_f32 v[108:109], v[108:109], v[116:117] op_sel_hi:[1,0]
	v_cvt_pk_bf16_f32 v115, v110, v111
	v_pk_mul_f32 v[110:111], v[110:111], v[116:117] op_sel_hi:[1,0]
	v_pk_mul_f32 v[106:107], v[134:135], v[106:107]
	v_pk_mul_f32 v[104:105], v[132:133], v[104:105]
	v_pk_mul_f32 v[108:109], v[128:129], v[108:109]
	global_store_dwordx4 v[172:173], v[112:115], off nt
	v_pk_mul_f32 v[110:111], v[130:131], v[110:111]
	v_cvt_pk_bf16_f32 v104, v104, v105
	v_cvt_pk_bf16_f32 v105, v106, v107
	v_cvt_pk_bf16_f32 v106, v108, v109
	s_nop 0
	v_cvt_pk_bf16_f32 v107, v110, v111
	ds_read_b32 v108, v209 offset:8384
	global_store_dwordx4 v[160:161], v[104:107], off sc1
	s_nop 1
	v_cvt_pk_bf16_f32 v104, v100, v101
	v_cvt_pk_bf16_f32 v105, v102, v103
	v_cvt_pk_bf16_f32 v106, v96, v97
	v_cvt_pk_bf16_f32 v107, v98, v99
	s_waitcnt lgkmcnt(0)
	v_pk_mul_f32 v[102:103], v[102:103], v[108:109] op_sel_hi:[1,0]
	v_pk_mul_f32 v[98:99], v[98:99], v[108:109] op_sel_hi:[1,0]
	v_pk_mul_f32 v[96:97], v[96:97], v[108:109] op_sel_hi:[1,0]
	global_store_dwordx4 v[174:175], v[104:107], off nt
	v_pk_mul_f32 v[100:101], v[100:101], v[108:109] op_sel_hi:[1,0]
	v_pk_mul_f32 v[102:103], v[134:135], v[102:103]
	v_pk_mul_f32 v[104:105], v[130:131], v[98:99]
	v_pk_mul_f32 v[98:99], v[128:129], v[96:97]
	v_pk_mul_f32 v[100:101], v[132:133], v[100:101]
	s_nop 0
	v_cvt_pk_bf16_f32 v96, v100, v101
	v_cvt_pk_bf16_f32 v97, v102, v103
	v_cvt_pk_bf16_f32 v98, v98, v99
	v_cvt_pk_bf16_f32 v99, v104, v105
	ds_read_b32 v102, v209 offset:8704
	v_lshl_add_u64 v[100:101], s[10:11], 0, v[166:167]
	global_store_dwordx4 v[100:101], v[96:99], off sc1
	s_nop 1
	v_lshlrev_b64 v[96:97], 10, v[142:143]
	v_lshl_add_u64 v[104:105], v[96:97], 0, v[200:201]
	v_lshlrev_b64 v[104:105], 1, v[104:105]
	v_cvt_pk_bf16_f32 v98, v92, v93
	v_cvt_pk_bf16_f32 v99, v94, v95
	v_cvt_pk_bf16_f32 v100, v88, v89
	v_cvt_pk_bf16_f32 v101, v90, v91
	v_lshl_add_u64 v[106:107], s[8:9], 0, v[104:105]
	s_waitcnt lgkmcnt(0)
	v_pk_mul_f32 v[94:95], v[94:95], v[102:103] op_sel_hi:[1,0]
	v_pk_mul_f32 v[90:91], v[90:91], v[102:103] op_sel_hi:[1,0]
	v_pk_mul_f32 v[88:89], v[88:89], v[102:103] op_sel_hi:[1,0]
	global_store_dwordx4 v[106:107], v[98:101], off nt
	v_pk_mul_f32 v[92:93], v[92:93], v[102:103] op_sel_hi:[1,0]
	v_pk_mul_f32 v[94:95], v[134:135], v[94:95]
	v_pk_mul_f32 v[98:99], v[130:131], v[90:91]
	v_pk_mul_f32 v[90:91], v[128:129], v[88:89]
	v_pk_mul_f32 v[92:93], v[132:133], v[92:93]
	s_nop 0
	v_cvt_pk_bf16_f32 v88, v92, v93
	v_cvt_pk_bf16_f32 v89, v94, v95
	v_cvt_pk_bf16_f32 v90, v90, v91
	v_cvt_pk_bf16_f32 v91, v98, v99
	ds_read_b32 v94, v209 offset:8768
	v_lshl_add_u64 v[92:93], s[10:11], 0, v[104:105]
	global_store_dwordx4 v[92:93], v[88:91], off sc1
	s_nop 1
	v_lshlrev_b64 v[88:89], 10, v[140:141]
	v_lshl_add_u64 v[98:99], v[88:89], 0, v[200:201]
	v_lshlrev_b64 v[98:99], 1, v[98:99]
	v_cvt_pk_bf16_f32 v90, v84, v85
	v_cvt_pk_bf16_f32 v91, v86, v87
	v_cvt_pk_bf16_f32 v92, v80, v81
	v_cvt_pk_bf16_f32 v93, v82, v83
	v_lshl_add_u64 v[100:101], s[8:9], 0, v[98:99]
	s_waitcnt lgkmcnt(0)
	v_pk_mul_f32 v[86:87], v[86:87], v[94:95] op_sel_hi:[1,0]
	v_pk_mul_f32 v[82:83], v[82:83], v[94:95] op_sel_hi:[1,0]
	v_pk_mul_f32 v[80:81], v[80:81], v[94:95] op_sel_hi:[1,0]
	global_store_dwordx4 v[100:101], v[90:93], off nt
	v_pk_mul_f32 v[84:85], v[84:85], v[94:95] op_sel_hi:[1,0]
	v_pk_mul_f32 v[86:87], v[134:135], v[86:87]
	v_pk_mul_f32 v[90:91], v[130:131], v[82:83]
	v_pk_mul_f32 v[82:83], v[128:129], v[80:81]
	v_pk_mul_f32 v[84:85], v[132:133], v[84:85]
	s_nop 0
	v_cvt_pk_bf16_f32 v80, v84, v85
	v_cvt_pk_bf16_f32 v81, v86, v87
	v_cvt_pk_bf16_f32 v82, v82, v83
	v_cvt_pk_bf16_f32 v83, v90, v91
	ds_read_b32 v86, v209 offset:8832
	v_lshl_add_u64 v[84:85], s[10:11], 0, v[98:99]
	global_store_dwordx4 v[84:85], v[80:83], off sc1
	s_nop 1
	v_lshlrev_b64 v[80:81], 10, v[138:139]
	v_lshl_add_u64 v[90:91], v[80:81], 0, v[200:201]
	v_lshlrev_b64 v[90:91], 1, v[90:91]
	v_cvt_pk_bf16_f32 v82, v76, v77
	v_cvt_pk_bf16_f32 v83, v78, v79
	v_cvt_pk_bf16_f32 v84, v72, v73
	v_cvt_pk_bf16_f32 v85, v74, v75
	v_lshl_add_u64 v[92:93], s[8:9], 0, v[90:91]
	s_waitcnt lgkmcnt(0)
	v_pk_mul_f32 v[78:79], v[78:79], v[86:87] op_sel_hi:[1,0]
	v_pk_mul_f32 v[74:75], v[74:75], v[86:87] op_sel_hi:[1,0]
	v_pk_mul_f32 v[72:73], v[72:73], v[86:87] op_sel_hi:[1,0]
	global_store_dwordx4 v[92:93], v[82:85], off nt
	v_pk_mul_f32 v[76:77], v[76:77], v[86:87] op_sel_hi:[1,0]
	v_pk_mul_f32 v[78:79], v[134:135], v[78:79]
	v_pk_mul_f32 v[82:83], v[130:131], v[74:75]
	v_pk_mul_f32 v[74:75], v[128:129], v[72:73]
	v_pk_mul_f32 v[76:77], v[132:133], v[76:77]
	s_nop 0
	v_cvt_pk_bf16_f32 v72, v76, v77
	v_cvt_pk_bf16_f32 v73, v78, v79
	v_cvt_pk_bf16_f32 v74, v74, v75
	v_cvt_pk_bf16_f32 v75, v82, v83
	ds_read_b32 v78, v209 offset:8896
	v_lshl_add_u64 v[76:77], s[10:11], 0, v[90:91]
	global_store_dwordx4 v[76:77], v[72:75], off sc1
	s_nop 1
	v_lshlrev_b64 v[72:73], 10, v[136:137]
	v_lshl_add_u64 v[82:83], v[72:73], 0, v[200:201]
	v_cvt_pk_bf16_f32 v74, v68, v69
	v_lshlrev_b64 v[82:83], 1, v[82:83]
	s_waitcnt lgkmcnt(0)
	v_pk_mul_f32 v[68:69], v[68:69], v[78:79] op_sel_hi:[1,0]
	v_cvt_pk_bf16_f32 v75, v70, v71
	v_cvt_pk_bf16_f32 v76, v64, v65
	v_cvt_pk_bf16_f32 v77, v66, v67
	v_lshl_add_u64 v[84:85], s[8:9], 0, v[82:83]
	v_pk_mul_f32 v[68:69], v[132:133], v[68:69]
	v_pk_mul_f32 v[66:67], v[66:67], v[78:79] op_sel_hi:[1,0]
	v_pk_mul_f32 v[64:65], v[64:65], v[78:79] op_sel_hi:[1,0]
	global_store_dwordx4 v[84:85], v[74:77], off nt
	v_pk_mul_f32 v[70:71], v[70:71], v[78:79] op_sel_hi:[1,0]
	v_or_b32_e32 v200, 0x80, v200
	v_pk_mul_f32 v[74:75], v[130:131], v[66:67]
	v_pk_mul_f32 v[66:67], v[128:129], v[64:65]
	v_cvt_pk_bf16_f32 v64, v68, v69
	v_lshl_add_u64 v[68:69], s[10:11], 0, v[82:83]
	v_pk_mul_f32 v[70:71], v[134:135], v[70:71]
	v_lshl_add_u64 v[82:83], v[144:145], 0, v[200:201]
	v_cvt_pk_bf16_f32 v65, v70, v71
	v_cvt_pk_bf16_f32 v66, v66, v67
	v_cvt_pk_bf16_f32 v67, v74, v75
	global_store_dwordx4 v[68:69], v[64:67], off sc1
	global_load_dwordx4 v[68:71], v[152:153], off offset:512
	s_nop 0
	global_load_dwordx4 v[64:67], v[152:153], off offset:528
	ds_read_b32 v78, v209 offset:8192
	v_cvt_pk_bf16_f32 v74, v60, v61
	v_lshlrev_b64 v[82:83], 1, v[82:83]
	v_cvt_pk_bf16_f32 v75, v62, v63
	v_cvt_pk_bf16_f32 v76, v56, v57
	s_waitcnt lgkmcnt(0)
	v_pk_mul_f32 v[60:61], v[60:61], v[78:79] op_sel_hi:[1,0]
	v_cvt_pk_bf16_f32 v77, v58, v59
	v_lshl_add_u64 v[84:85], s[8:9], 0, v[82:83]
	v_pk_mul_f32 v[58:59], v[58:59], v[78:79] op_sel_hi:[1,0]
	v_pk_mul_f32 v[56:57], v[56:57], v[78:79] op_sel_hi:[1,0]
	global_store_dwordx4 v[84:85], v[74:77], off nt
	v_pk_mul_f32 v[62:63], v[62:63], v[78:79] op_sel_hi:[1,0]
	s_waitcnt vmcnt(2)
	v_pk_mul_f32 v[60:61], v[68:69], v[60:61]
	s_waitcnt vmcnt(1)
	v_pk_mul_f32 v[74:75], v[66:67], v[58:59]
	v_pk_mul_f32 v[58:59], v[64:65], v[56:57]
	v_cvt_pk_bf16_f32 v56, v60, v61
	v_lshl_add_u64 v[60:61], s[10:11], 0, v[82:83]
	v_pk_mul_f32 v[62:63], v[70:71], v[62:63]
	s_nop 0
	v_cvt_pk_bf16_f32 v57, v62, v63
	v_cvt_pk_bf16_f32 v58, v58, v59
	v_cvt_pk_bf16_f32 v59, v74, v75
	global_store_dwordx4 v[60:61], v[56:59], off sc1
	ds_read_b32 v60, v209 offset:8256
	v_lshl_add_u64 v[62:63], v[150:151], 0, v[200:201]
	v_cvt_pk_bf16_f32 v56, v52, v53
	v_lshlrev_b64 v[62:63], 1, v[62:63]
	v_cvt_pk_bf16_f32 v57, v54, v55
	s_waitcnt lgkmcnt(0)
	v_pk_mul_f32 v[52:53], v[52:53], v[60:61] op_sel_hi:[1,0]
	v_cvt_pk_bf16_f32 v58, v48, v49
	v_cvt_pk_bf16_f32 v59, v50, v51
	v_lshl_add_u64 v[74:75], s[8:9], 0, v[62:63]
	v_pk_mul_f32 v[52:53], v[68:69], v[52:53]
	v_pk_mul_f32 v[50:51], v[50:51], v[60:61] op_sel_hi:[1,0]
	v_pk_mul_f32 v[48:49], v[48:49], v[60:61] op_sel_hi:[1,0]
	global_store_dwordx4 v[74:75], v[56:59], off nt
	v_pk_mul_f32 v[54:55], v[54:55], v[60:61] op_sel_hi:[1,0]
	s_nop 0
	v_pk_mul_f32 v[56:57], v[66:67], v[50:51]
	v_pk_mul_f32 v[50:51], v[64:65], v[48:49]
	v_cvt_pk_bf16_f32 v48, v52, v53
	v_lshl_add_u64 v[52:53], s[10:11], 0, v[62:63]
	v_pk_mul_f32 v[54:55], v[70:71], v[54:55]
	s_nop 0
	v_cvt_pk_bf16_f32 v49, v54, v55
	v_cvt_pk_bf16_f32 v50, v50, v51
	v_cvt_pk_bf16_f32 v51, v56, v57
	global_store_dwordx4 v[52:53], v[48:51], off sc1
	ds_read_b32 v52, v209 offset:8320
	v_lshl_add_u64 v[54:55], v[148:149], 0, v[200:201]
	v_cvt_pk_bf16_f32 v48, v44, v45
	v_lshlrev_b64 v[54:55], 1, v[54:55]
	v_cvt_pk_bf16_f32 v49, v46, v47
	s_waitcnt lgkmcnt(0)
	v_pk_mul_f32 v[44:45], v[44:45], v[52:53] op_sel_hi:[1,0]
	v_cvt_pk_bf16_f32 v50, v40, v41
	v_cvt_pk_bf16_f32 v51, v42, v43
	v_lshl_add_u64 v[56:57], s[8:9], 0, v[54:55]
	v_pk_mul_f32 v[44:45], v[68:69], v[44:45]
	v_pk_mul_f32 v[42:43], v[42:43], v[52:53] op_sel_hi:[1,0]
	v_pk_mul_f32 v[40:41], v[40:41], v[52:53] op_sel_hi:[1,0]
	global_store_dwordx4 v[56:57], v[48:51], off nt
	v_pk_mul_f32 v[46:47], v[46:47], v[52:53] op_sel_hi:[1,0]
	s_nop 0
	v_pk_mul_f32 v[48:49], v[66:67], v[42:43]
	v_pk_mul_f32 v[42:43], v[64:65], v[40:41]
	v_cvt_pk_bf16_f32 v40, v44, v45
	v_lshl_add_u64 v[44:45], s[10:11], 0, v[54:55]
	v_pk_mul_f32 v[46:47], v[70:71], v[46:47]
	s_nop 0
	v_cvt_pk_bf16_f32 v41, v46, v47
	v_cvt_pk_bf16_f32 v42, v42, v43
	v_cvt_pk_bf16_f32 v43, v48, v49
	global_store_dwordx4 v[44:45], v[40:43], off sc1
	ds_read_b32 v44, v209 offset:8384
	v_lshl_add_u64 v[46:47], v[146:147], 0, v[200:201]
	v_cvt_pk_bf16_f32 v40, v36, v37
	v_lshlrev_b64 v[46:47], 1, v[46:47]
	v_cvt_pk_bf16_f32 v41, v38, v39
	s_waitcnt lgkmcnt(0)
	v_pk_mul_f32 v[36:37], v[36:37], v[44:45] op_sel_hi:[1,0]
	v_cvt_pk_bf16_f32 v42, v32, v33
	v_cvt_pk_bf16_f32 v43, v34, v35
	v_lshl_add_u64 v[48:49], s[8:9], 0, v[46:47]
	v_pk_mul_f32 v[36:37], v[68:69], v[36:37]
	v_pk_mul_f32 v[34:35], v[34:35], v[44:45] op_sel_hi:[1,0]
	v_pk_mul_f32 v[32:33], v[32:33], v[44:45] op_sel_hi:[1,0]
	global_store_dwordx4 v[48:49], v[40:43], off nt
	v_pk_mul_f32 v[38:39], v[38:39], v[44:45] op_sel_hi:[1,0]
	s_nop 0
	v_pk_mul_f32 v[40:41], v[66:67], v[34:35]
	v_pk_mul_f32 v[34:35], v[64:65], v[32:33]
	v_cvt_pk_bf16_f32 v32, v36, v37
	v_lshl_add_u64 v[36:37], s[10:11], 0, v[46:47]
	v_pk_mul_f32 v[38:39], v[70:71], v[38:39]
	s_nop 0
	v_cvt_pk_bf16_f32 v33, v38, v39
	v_cvt_pk_bf16_f32 v34, v34, v35
	v_cvt_pk_bf16_f32 v35, v40, v41
	global_store_dwordx4 v[36:37], v[32:35], off sc1
	ds_read_b32 v36, v209 offset:8704
	v_lshl_add_u64 v[38:39], v[96:97], 0, v[200:201]
	v_cvt_pk_bf16_f32 v32, v28, v29
	v_lshlrev_b64 v[38:39], 1, v[38:39]
	v_cvt_pk_bf16_f32 v33, v30, v31
	s_waitcnt lgkmcnt(0)
	v_pk_mul_f32 v[28:29], v[28:29], v[36:37] op_sel_hi:[1,0]
	v_cvt_pk_bf16_f32 v34, v24, v25
	v_cvt_pk_bf16_f32 v35, v26, v27
	v_lshl_add_u64 v[40:41], s[8:9], 0, v[38:39]
	v_pk_mul_f32 v[28:29], v[68:69], v[28:29]
	v_pk_mul_f32 v[26:27], v[26:27], v[36:37] op_sel_hi:[1,0]
	v_pk_mul_f32 v[24:25], v[24:25], v[36:37] op_sel_hi:[1,0]
	global_store_dwordx4 v[40:41], v[32:35], off nt
	v_pk_mul_f32 v[30:31], v[30:31], v[36:37] op_sel_hi:[1,0]
	s_nop 0
	v_pk_mul_f32 v[32:33], v[66:67], v[26:27]
	v_pk_mul_f32 v[26:27], v[64:65], v[24:25]
	v_cvt_pk_bf16_f32 v24, v28, v29
	v_lshl_add_u64 v[28:29], s[10:11], 0, v[38:39]
	v_pk_mul_f32 v[30:31], v[70:71], v[30:31]
	s_nop 0
	v_cvt_pk_bf16_f32 v25, v30, v31
	v_cvt_pk_bf16_f32 v26, v26, v27
	v_cvt_pk_bf16_f32 v27, v32, v33
	global_store_dwordx4 v[28:29], v[24:27], off sc1
	ds_read_b32 v28, v209 offset:8768
	v_lshl_add_u64 v[30:31], v[88:89], 0, v[200:201]
	v_cvt_pk_bf16_f32 v24, v20, v21
	v_lshlrev_b64 v[30:31], 1, v[30:31]
	v_cvt_pk_bf16_f32 v25, v22, v23
	s_waitcnt lgkmcnt(0)
	v_pk_mul_f32 v[20:21], v[20:21], v[28:29] op_sel_hi:[1,0]
	v_cvt_pk_bf16_f32 v26, v16, v17
	v_cvt_pk_bf16_f32 v27, v18, v19
	v_lshl_add_u64 v[32:33], s[8:9], 0, v[30:31]
	v_pk_mul_f32 v[20:21], v[68:69], v[20:21]
	v_pk_mul_f32 v[18:19], v[18:19], v[28:29] op_sel_hi:[1,0]
	v_pk_mul_f32 v[16:17], v[16:17], v[28:29] op_sel_hi:[1,0]
	global_store_dwordx4 v[32:33], v[24:27], off nt
	v_pk_mul_f32 v[22:23], v[22:23], v[28:29] op_sel_hi:[1,0]
	s_nop 0
	v_pk_mul_f32 v[24:25], v[66:67], v[18:19]
	v_pk_mul_f32 v[18:19], v[64:65], v[16:17]
	v_cvt_pk_bf16_f32 v16, v20, v21
	v_lshl_add_u64 v[20:21], s[10:11], 0, v[30:31]
	v_pk_mul_f32 v[22:23], v[70:71], v[22:23]
	s_nop 0
	v_cvt_pk_bf16_f32 v17, v22, v23
	v_cvt_pk_bf16_f32 v18, v18, v19
	v_cvt_pk_bf16_f32 v19, v24, v25
	global_store_dwordx4 v[20:21], v[16:19], off sc1
	ds_read_b32 v20, v209 offset:8832
	v_lshl_add_u64 v[22:23], v[80:81], 0, v[200:201]
	v_cvt_pk_bf16_f32 v16, v12, v13
	v_lshlrev_b64 v[22:23], 1, v[22:23]
	v_cvt_pk_bf16_f32 v17, v14, v15
	s_waitcnt lgkmcnt(0)
	v_pk_mul_f32 v[12:13], v[12:13], v[20:21] op_sel_hi:[1,0]
	v_cvt_pk_bf16_f32 v18, v8, v9
	v_cvt_pk_bf16_f32 v19, v10, v11
	v_lshl_add_u64 v[24:25], s[8:9], 0, v[22:23]
	v_pk_mul_f32 v[12:13], v[68:69], v[12:13]
	v_pk_mul_f32 v[10:11], v[10:11], v[20:21] op_sel_hi:[1,0]
	v_pk_mul_f32 v[8:9], v[8:9], v[20:21] op_sel_hi:[1,0]
	global_store_dwordx4 v[24:25], v[16:19], off nt
	v_pk_mul_f32 v[14:15], v[14:15], v[20:21] op_sel_hi:[1,0]
	s_nop 0
	v_pk_mul_f32 v[16:17], v[66:67], v[10:11]
	v_pk_mul_f32 v[10:11], v[64:65], v[8:9]
	v_cvt_pk_bf16_f32 v8, v12, v13
	v_lshl_add_u64 v[12:13], s[10:11], 0, v[22:23]
	v_pk_mul_f32 v[14:15], v[70:71], v[14:15]
	s_nop 0
	v_cvt_pk_bf16_f32 v9, v14, v15
	v_cvt_pk_bf16_f32 v10, v10, v11
	v_cvt_pk_bf16_f32 v11, v16, v17
	global_store_dwordx4 v[12:13], v[8:11], off sc1
	ds_read_b32 v12, v209 offset:8896
	v_lshl_add_u64 v[14:15], v[72:73], 0, v[200:201]
	v_cvt_pk_bf16_f32 v8, v4, v5
	v_lshlrev_b64 v[14:15], 1, v[14:15]
	v_cvt_pk_bf16_f32 v9, v6, v7
	s_waitcnt lgkmcnt(0)
	v_pk_mul_f32 v[4:5], v[4:5], v[12:13] op_sel_hi:[1,0]
	v_cvt_pk_bf16_f32 v10, v0, v1
	v_cvt_pk_bf16_f32 v11, v2, v3
	v_lshl_add_u64 v[16:17], s[8:9], 0, v[14:15]
	v_pk_mul_f32 v[4:5], v[68:69], v[4:5]
	v_pk_mul_f32 v[2:3], v[2:3], v[12:13] op_sel_hi:[1,0]
	v_pk_mul_f32 v[0:1], v[0:1], v[12:13] op_sel_hi:[1,0]
	global_store_dwordx4 v[16:17], v[8:11], off nt
	v_pk_mul_f32 v[6:7], v[6:7], v[12:13] op_sel_hi:[1,0]
	s_nop 0
	v_pk_mul_f32 v[8:9], v[66:67], v[2:3]
	v_pk_mul_f32 v[2:3], v[64:65], v[0:1]
	v_cvt_pk_bf16_f32 v0, v4, v5
	v_lshl_add_u64 v[4:5], s[10:11], 0, v[14:15]
	v_pk_mul_f32 v[6:7], v[70:71], v[6:7]
	s_nop 0
	v_cvt_pk_bf16_f32 v1, v6, v7
	v_cvt_pk_bf16_f32 v2, v2, v3
	v_cvt_pk_bf16_f32 v3, v8, v9
	global_store_dwordx4 v[4:5], v[0:3], off sc1

.LBB0_1000:
	s_or_b64 exec, exec, s[10:11]
	s_waitcnt lgkmcnt(0)
	s_barrier
	s_waitcnt lgkmcnt(0)
	v_lshl_add_u64 v[202:203], v[200:201], 2, s[34:35]
	global_load_dwordx4 v[196:199], v[202:203], off
	global_load_dwordx4 v[192:195], v[202:203], off offset:16
	v_lshl_add_u32 v206, v204, 2, 0
	ds_read_b32 v224, v206 offset:8192
	s_waitcnt vmcnt(0)
	v_lshlrev_b32_e32 v208, 16, v188
	v_and_b32_e32 v209, 0xffff0000, v188
	v_lshlrev_b32_e32 v210, 16, v189
	v_and_b32_e32 v211, 0xffff0000, v189
	s_waitcnt lgkmcnt(0)
	v_pk_mul_f32 v[126:127], v[126:127], v[224:225] op_sel_hi:[1,0]
	v_pk_mul_f32 v[124:125], v[124:125], v[224:225] op_sel_hi:[1,0]
	v_lshlrev_b32_e32 v212, 16, v190
	v_and_b32_e32 v213, 0xffff0000, v190
	v_lshlrev_b32_e32 v190, 16, v191
	v_and_b32_e32 v191, 0xffff0000, v191
	v_pk_mul_f32 v[122:123], v[122:123], v[224:225] op_sel_hi:[1,0]
	v_pk_mul_f32 v[120:121], v[120:121], v[224:225] op_sel_hi:[1,0]
	v_add_u32_e32 v204, s26, v204
	v_add_u32_e32 v226, 16, v204
	s_add_u32 s8, s18, 0x24800000
	v_ashrrev_i32_e32 v205, 31, v204
	v_ashrrev_i32_e32 v227, 31, v226
	s_addc_u32 s9, s19, 0
	v_lshlrev_b64 v[228:229], 11, v[204:205]
	v_lshlrev_b64 v[226:227], 11, v[226:227]
	v_lshlrev_b64 v[188:189], 1, v[200:201]
	v_lshl_add_u64 v[228:229], s[8:9], 0, v[228:229]
	v_lshlrev_b32_e32 v200, 16, v184
	v_and_b32_e32 v201, 0xffff0000, v184
	v_lshlrev_b32_e32 v184, 16, v185
	v_and_b32_e32 v185, 0xffff0000, v185
	v_lshlrev_b32_e32 v214, 16, v186
	v_and_b32_e32 v215, 0xffff0000, v186
	v_lshlrev_b32_e32 v186, 16, v187
	v_and_b32_e32 v187, 0xffff0000, v187
	v_lshlrev_b32_e32 v216, 16, v180
	v_and_b32_e32 v217, 0xffff0000, v180
	v_lshlrev_b32_e32 v180, 16, v181
	v_and_b32_e32 v181, 0xffff0000, v181
	v_lshlrev_b32_e32 v218, 16, v182
	v_and_b32_e32 v219, 0xffff0000, v182
	v_lshlrev_b32_e32 v182, 16, v183
	v_and_b32_e32 v183, 0xffff0000, v183
	v_lshlrev_b32_e32 v220, 16, v176
	v_and_b32_e32 v221, 0xffff0000, v176
	v_lshlrev_b32_e32 v222, 16, v178
	v_and_b32_e32 v223, 0xffff0000, v178
	v_lshlrev_b32_e32 v176, 16, v177
	v_and_b32_e32 v177, 0xffff0000, v177
	v_lshlrev_b32_e32 v178, 16, v179
	v_and_b32_e32 v179, 0xffff0000, v179
	v_pk_fma_f32 v[124:125], v[196:197], v[124:125], v[208:209]
	v_pk_fma_f32 v[126:127], v[198:199], v[126:127], v[210:211]
	v_pk_fma_f32 v[120:121], v[192:193], v[120:121], v[212:213]
	v_pk_fma_f32 v[122:123], v[194:195], v[122:123], v[190:191]
	v_cvt_pk_bf16_f32 v124, v124, v125
	v_cvt_pk_bf16_f32 v125, v126, v127
	v_cvt_pk_bf16_f32 v126, v120, v121
	v_lshl_add_u64 v[120:121], s[8:9], 0, v[226:227]
	v_cvt_pk_bf16_f32 v127, v122, v123
	ds_read_b32 v190, v206 offset:8256
	v_lshl_add_u64 v[122:123], v[228:229], 0, v[188:189]
	v_lshl_add_u64 v[120:121], v[120:121], 0, v[188:189]
	global_store_dwordx4 v[122:123], v[124:127], off sc1
	s_waitcnt lgkmcnt(0)
	v_pk_mul_f32 v[118:119], v[118:119], v[190:191] op_sel_hi:[1,0]
	v_pk_mul_f32 v[116:117], v[116:117], v[190:191] op_sel_hi:[1,0]
	v_pk_mul_f32 v[114:115], v[114:115], v[190:191] op_sel_hi:[1,0]
	v_pk_mul_f32 v[112:113], v[112:113], v[190:191] op_sel_hi:[1,0]
	v_pk_fma_f32 v[116:117], v[196:197], v[116:117], v[200:201]
	v_pk_fma_f32 v[118:119], v[198:199], v[118:119], v[184:185]
	v_pk_fma_f32 v[124:125], v[192:193], v[112:113], v[214:215]
	v_pk_fma_f32 v[126:127], v[194:195], v[114:115], v[186:187]
	v_cvt_pk_bf16_f32 v112, v116, v117
	v_cvt_pk_bf16_f32 v113, v118, v119
	v_cvt_pk_bf16_f32 v114, v124, v125
	v_add_u32_e32 v116, 48, v204
	v_cvt_pk_bf16_f32 v115, v126, v127
	global_store_dwordx4 v[120:121], v[112:115], off sc1
	ds_read_b32 v112, v206 offset:8320
	v_ashrrev_i32_e32 v117, 31, v116
	v_add_u32_e32 v114, 32, v204
	v_ashrrev_i32_e32 v115, 31, v114
	s_waitcnt lgkmcnt(0)
	v_pk_mul_f32 v[110:111], v[110:111], v[112:113] op_sel_hi:[1,0]
	v_pk_mul_f32 v[108:109], v[108:109], v[112:113] op_sel_hi:[1,0]
	v_pk_mul_f32 v[106:107], v[106:107], v[112:113] op_sel_hi:[1,0]
	v_pk_mul_f32 v[104:105], v[104:105], v[112:113] op_sel_hi:[1,0]
	v_pk_fma_f32 v[108:109], v[196:197], v[108:109], v[216:217]
	v_pk_fma_f32 v[110:111], v[198:199], v[110:111], v[180:181]
	v_pk_fma_f32 v[104:105], v[192:193], v[104:105], v[218:219]
	v_pk_fma_f32 v[112:113], v[194:195], v[106:107], v[182:183]
	v_cvt_pk_bf16_f32 v106, v108, v109
	v_cvt_pk_bf16_f32 v107, v110, v111
	v_cvt_pk_bf16_f32 v108, v104, v105
	v_lshlrev_b64 v[104:105], 11, v[114:115]
	v_cvt_pk_bf16_f32 v109, v112, v113
	ds_read_b32 v110, v206 offset:8384
	v_lshl_add_u64 v[104:105], s[8:9], 0, v[104:105]
	v_lshl_add_u64 v[104:105], v[104:105], 0, v[188:189]
	global_store_dwordx4 v[104:105], v[106:109], off sc1
	s_waitcnt lgkmcnt(0)
	v_pk_mul_f32 v[100:101], v[100:101], v[110:111] op_sel_hi:[1,0]
	v_pk_mul_f32 v[96:97], v[96:97], v[110:111] op_sel_hi:[1,0]
	v_pk_mul_f32 v[102:103], v[102:103], v[110:111] op_sel_hi:[1,0]
	v_pk_fma_f32 v[100:101], v[196:197], v[100:101], v[220:221]
	v_pk_mul_f32 v[98:99], v[98:99], v[110:111] op_sel_hi:[1,0]
	v_pk_fma_f32 v[96:97], v[192:193], v[96:97], v[222:223]
	v_pk_fma_f32 v[102:103], v[198:199], v[102:103], v[176:177]
	v_pk_fma_f32 v[106:107], v[194:195], v[98:99], v[178:179]
	v_cvt_pk_bf16_f32 v98, v100, v101
	v_cvt_pk_bf16_f32 v99, v102, v103
	v_cvt_pk_bf16_f32 v100, v96, v97
	v_lshlrev_b64 v[96:97], 11, v[116:117]
	v_lshl_add_u64 v[96:97], s[8:9], 0, v[96:97]
	v_lshl_add_u64 v[96:97], v[96:97], 0, v[188:189]
	v_cvt_pk_bf16_f32 v101, v106, v107
	global_store_dwordx4 v[96:97], v[98:101], off sc1
	ds_read_b32 v98, v206 offset:8704
	v_lshlrev_b32_e32 v102, 16, v172
	v_add_u32_e32 v100, 0x80, v204
	v_and_b32_e32 v103, 0xffff0000, v172
	v_lshlrev_b32_e32 v108, 16, v174
	v_and_b32_e32 v109, 0xffff0000, v174
	s_waitcnt lgkmcnt(0)
	v_pk_mul_f32 v[92:93], v[92:93], v[98:99] op_sel_hi:[1,0]
	v_pk_mul_f32 v[88:89], v[88:89], v[98:99] op_sel_hi:[1,0]
	v_ashrrev_i32_e32 v101, 31, v100
	v_lshlrev_b32_e32 v106, 16, v173
	v_and_b32_e32 v107, 0xffff0000, v173
	v_lshlrev_b32_e32 v110, 16, v175
	v_and_b32_e32 v111, 0xffff0000, v175
	v_pk_mul_f32 v[94:95], v[94:95], v[98:99] op_sel_hi:[1,0]
	v_pk_fma_f32 v[92:93], v[196:197], v[92:93], v[102:103]
	v_pk_mul_f32 v[90:91], v[90:91], v[98:99] op_sel_hi:[1,0]
	v_pk_fma_f32 v[88:89], v[192:193], v[88:89], v[108:109]
	v_pk_fma_f32 v[94:95], v[198:199], v[94:95], v[106:107]
	v_pk_fma_f32 v[98:99], v[194:195], v[90:91], v[110:111]
	v_cvt_pk_bf16_f32 v90, v92, v93
	v_cvt_pk_bf16_f32 v91, v94, v95
	v_cvt_pk_bf16_f32 v92, v88, v89
	v_lshlrev_b64 v[88:89], 11, v[100:101]
	v_lshl_add_u64 v[88:89], s[8:9], 0, v[88:89]
	v_lshl_add_u64 v[88:89], v[88:89], 0, v[188:189]
	v_cvt_pk_bf16_f32 v93, v98, v99
	global_store_dwordx4 v[88:89], v[90:93], off sc1
	ds_read_b32 v90, v206 offset:8768
	v_lshlrev_b32_e32 v94, 16, v168
	v_add_u32_e32 v92, 0x90, v204
	v_and_b32_e32 v95, 0xffff0000, v168
	v_lshlrev_b32_e32 v100, 16, v170
	v_and_b32_e32 v101, 0xffff0000, v170
	s_waitcnt lgkmcnt(0)
	v_pk_mul_f32 v[84:85], v[84:85], v[90:91] op_sel_hi:[1,0]
	v_pk_mul_f32 v[80:81], v[80:81], v[90:91] op_sel_hi:[1,0]
	v_ashrrev_i32_e32 v93, 31, v92
	v_lshlrev_b32_e32 v98, 16, v169
	v_and_b32_e32 v99, 0xffff0000, v169
	v_lshlrev_b32_e32 v102, 16, v171
	v_and_b32_e32 v103, 0xffff0000, v171
	v_pk_mul_f32 v[86:87], v[86:87], v[90:91] op_sel_hi:[1,0]
	v_pk_fma_f32 v[84:85], v[196:197], v[84:85], v[94:95]
	v_pk_mul_f32 v[82:83], v[82:83], v[90:91] op_sel_hi:[1,0]
	v_pk_fma_f32 v[80:81], v[192:193], v[80:81], v[100:101]
	v_pk_fma_f32 v[86:87], v[198:199], v[86:87], v[98:99]
	v_pk_fma_f32 v[90:91], v[194:195], v[82:83], v[102:103]
	v_cvt_pk_bf16_f32 v82, v84, v85
	v_cvt_pk_bf16_f32 v83, v86, v87
	v_cvt_pk_bf16_f32 v84, v80, v81
	v_lshlrev_b64 v[80:81], 11, v[92:93]
	v_lshl_add_u64 v[80:81], s[8:9], 0, v[80:81]
	v_lshl_add_u64 v[80:81], v[80:81], 0, v[188:189]
	v_cvt_pk_bf16_f32 v85, v90, v91
	global_store_dwordx4 v[80:81], v[82:85], off sc1
	ds_read_b32 v82, v206 offset:8832
	v_lshlrev_b32_e32 v86, 16, v164
	v_add_u32_e32 v84, 0xa0, v204
	v_and_b32_e32 v87, 0xffff0000, v164
	v_lshlrev_b32_e32 v92, 16, v166
	v_and_b32_e32 v93, 0xffff0000, v166
	s_waitcnt lgkmcnt(0)
	v_pk_mul_f32 v[76:77], v[76:77], v[82:83] op_sel_hi:[1,0]
	v_pk_mul_f32 v[72:73], v[72:73], v[82:83] op_sel_hi:[1,0]
	v_ashrrev_i32_e32 v85, 31, v84
	v_lshlrev_b32_e32 v90, 16, v165
	v_and_b32_e32 v91, 0xffff0000, v165
	v_lshlrev_b32_e32 v94, 16, v167
	v_and_b32_e32 v95, 0xffff0000, v167
	v_pk_mul_f32 v[78:79], v[78:79], v[82:83] op_sel_hi:[1,0]
	v_pk_fma_f32 v[76:77], v[196:197], v[76:77], v[86:87]
	v_pk_mul_f32 v[74:75], v[74:75], v[82:83] op_sel_hi:[1,0]
	v_pk_fma_f32 v[72:73], v[192:193], v[72:73], v[92:93]
	v_pk_fma_f32 v[78:79], v[198:199], v[78:79], v[90:91]
	v_pk_fma_f32 v[82:83], v[194:195], v[74:75], v[94:95]
	v_cvt_pk_bf16_f32 v74, v76, v77
	v_cvt_pk_bf16_f32 v75, v78, v79
	v_cvt_pk_bf16_f32 v76, v72, v73
	v_lshlrev_b64 v[72:73], 11, v[84:85]
	v_lshl_add_u64 v[72:73], s[8:9], 0, v[72:73]
	v_lshl_add_u64 v[72:73], v[72:73], 0, v[188:189]
	v_cvt_pk_bf16_f32 v77, v82, v83
	global_store_dwordx4 v[72:73], v[74:77], off sc1
	ds_read_b32 v74, v206 offset:8896
	v_lshlrev_b32_e32 v78, 16, v160
	v_add_u32_e32 v76, 0xb0, v204
	v_and_b32_e32 v79, 0xffff0000, v160
	v_ashrrev_i32_e32 v77, 31, v76
	s_waitcnt lgkmcnt(0)
	v_pk_mul_f32 v[68:69], v[68:69], v[74:75] op_sel_hi:[1,0]
	v_lshlrev_b32_e32 v84, 16, v162
	v_and_b32_e32 v85, 0xffff0000, v162
	v_pk_fma_f32 v[68:69], v[196:197], v[68:69], v[78:79]
	v_pk_mul_f32 v[64:65], v[64:65], v[74:75] op_sel_hi:[1,0]
	v_pk_mul_f32 v[70:71], v[70:71], v[74:75] op_sel_hi:[1,0]
	v_pk_mul_f32 v[66:67], v[66:67], v[74:75] op_sel_hi:[1,0]
	v_pk_fma_f32 v[74:75], v[192:193], v[64:65], v[84:85]
	v_cvt_pk_bf16_f32 v64, v68, v69
	v_lshlrev_b64 v[68:69], 11, v[76:77]
	v_lshlrev_b32_e32 v82, 16, v161
	v_and_b32_e32 v83, 0xffff0000, v161
	v_lshlrev_b32_e32 v86, 16, v163
	v_and_b32_e32 v87, 0xffff0000, v163
	v_lshl_add_u64 v[68:69], s[8:9], 0, v[68:69]
	v_pk_fma_f32 v[70:71], v[198:199], v[70:71], v[82:83]
	v_pk_fma_f32 v[78:79], v[194:195], v[66:67], v[86:87]
	v_cvt_pk_bf16_f32 v65, v70, v71
	v_cvt_pk_bf16_f32 v66, v74, v75
	v_lshl_add_u64 v[74:75], v[68:69], 0, v[188:189]
	v_cvt_pk_bf16_f32 v67, v78, v79
	global_store_dwordx4 v[74:75], v[64:67], off sc1
	global_load_dwordx4 v[68:71], v[202:203], off offset:512
	global_load_dwordx4 v[64:67], v[202:203], off offset:528
	ds_read_b32 v76, v206 offset:8192
	v_lshlrev_b32_e32 v78, 16, v156
	v_and_b32_e32 v79, 0xffff0000, v156
	v_lshlrev_b32_e32 v84, 16, v158
	v_and_b32_e32 v85, 0xffff0000, v158
	s_waitcnt lgkmcnt(0)
	v_pk_mul_f32 v[60:61], v[60:61], v[76:77] op_sel_hi:[1,0]
	v_pk_mul_f32 v[56:57], v[56:57], v[76:77] op_sel_hi:[1,0]
	v_lshlrev_b32_e32 v82, 16, v157
	v_and_b32_e32 v83, 0xffff0000, v157
	v_lshlrev_b32_e32 v86, 16, v159
	v_and_b32_e32 v87, 0xffff0000, v159
	v_pk_mul_f32 v[62:63], v[62:63], v[76:77] op_sel_hi:[1,0]
	v_pk_mul_f32 v[58:59], v[58:59], v[76:77] op_sel_hi:[1,0]
	s_waitcnt vmcnt(1)
	v_pk_fma_f32 v[60:61], v[68:69], v[60:61], v[78:79]
	s_waitcnt vmcnt(0)
	v_pk_fma_f32 v[76:77], v[64:65], v[56:57], v[84:85]
	v_cvt_pk_bf16_f32 v56, v60, v61
	v_pk_fma_f32 v[62:63], v[70:71], v[62:63], v[82:83]
	v_pk_fma_f32 v[78:79], v[66:67], v[58:59], v[86:87]
	v_cvt_pk_bf16_f32 v57, v62, v63
	v_cvt_pk_bf16_f32 v58, v76, v77
	v_lshlrev_b32_e32 v60, 16, v153
	v_cvt_pk_bf16_f32 v59, v78, v79
	global_store_dwordx4 v[122:123], v[56:59], off offset:256 sc1
	ds_read_b32 v56, v206 offset:8256
	v_and_b32_e32 v61, 0xffff0000, v153
	v_lshlrev_b32_e32 v58, 16, v152
	v_and_b32_e32 v59, 0xffff0000, v152
	v_lshlrev_b32_e32 v62, 16, v154
	v_and_b32_e32 v63, 0xffff0000, v154
	v_lshlrev_b32_e32 v76, 16, v155
	v_and_b32_e32 v77, 0xffff0000, v155
	s_waitcnt lgkmcnt(0)
	v_pk_mul_f32 v[54:55], v[54:55], v[56:57] op_sel_hi:[1,0]
	v_pk_mul_f32 v[52:53], v[52:53], v[56:57] op_sel_hi:[1,0]
	v_pk_mul_f32 v[50:51], v[50:51], v[56:57] op_sel_hi:[1,0]
	v_pk_mul_f32 v[48:49], v[48:49], v[56:57] op_sel_hi:[1,0]
	v_pk_fma_f32 v[52:53], v[68:69], v[52:53], v[58:59]
	v_pk_fma_f32 v[54:55], v[70:71], v[54:55], v[60:61]
	v_pk_fma_f32 v[56:57], v[64:65], v[48:49], v[62:63]
	v_pk_fma_f32 v[58:59], v[66:67], v[50:51], v[76:77]
	v_cvt_pk_bf16_f32 v48, v52, v53
	v_cvt_pk_bf16_f32 v49, v54, v55
	v_cvt_pk_bf16_f32 v50, v56, v57
	v_lshlrev_b32_e32 v54, 16, v150
	v_cvt_pk_bf16_f32 v51, v58, v59
	global_store_dwordx4 v[120:121], v[48:51], off offset:256 sc1
	ds_read_b32 v48, v206 offset:8320
	v_and_b32_e32 v55, 0xffff0000, v150
	v_lshlrev_b32_e32 v50, 16, v148
	v_and_b32_e32 v51, 0xffff0000, v148
	v_lshlrev_b32_e32 v52, 16, v149
	s_waitcnt lgkmcnt(0)
	v_pk_mul_f32 v[44:45], v[44:45], v[48:49] op_sel_hi:[1,0]
	v_pk_mul_f32 v[40:41], v[40:41], v[48:49] op_sel_hi:[1,0]
	v_and_b32_e32 v53, 0xffff0000, v149
	v_lshlrev_b32_e32 v56, 16, v151
	v_and_b32_e32 v57, 0xffff0000, v151
	v_pk_mul_f32 v[46:47], v[46:47], v[48:49] op_sel_hi:[1,0]
	v_pk_fma_f32 v[44:45], v[68:69], v[44:45], v[50:51]
	v_pk_mul_f32 v[42:43], v[42:43], v[48:49] op_sel_hi:[1,0]
	v_pk_fma_f32 v[48:49], v[64:65], v[40:41], v[54:55]
	v_cvt_pk_bf16_f32 v40, v44, v45
	v_pk_fma_f32 v[46:47], v[70:71], v[46:47], v[52:53]
	v_pk_fma_f32 v[50:51], v[66:67], v[42:43], v[56:57]
	v_cvt_pk_bf16_f32 v41, v46, v47
	v_cvt_pk_bf16_f32 v42, v48, v49
	v_lshlrev_b32_e32 v44, 16, v145
	v_cvt_pk_bf16_f32 v43, v50, v51
	global_store_dwordx4 v[104:105], v[40:43], off offset:256 sc1
	ds_read_b32 v40, v206 offset:8384
	v_and_b32_e32 v45, 0xffff0000, v145
	v_lshlrev_b32_e32 v42, 16, v144
	v_and_b32_e32 v43, 0xffff0000, v144
	v_lshlrev_b32_e32 v46, 16, v146
	v_and_b32_e32 v47, 0xffff0000, v146
	v_lshlrev_b32_e32 v48, 16, v147
	v_and_b32_e32 v49, 0xffff0000, v147
	s_waitcnt lgkmcnt(0)
	v_pk_mul_f32 v[38:39], v[38:39], v[40:41] op_sel_hi:[1,0]
	v_pk_mul_f32 v[36:37], v[36:37], v[40:41] op_sel_hi:[1,0]
	v_pk_mul_f32 v[34:35], v[34:35], v[40:41] op_sel_hi:[1,0]
	v_pk_mul_f32 v[32:33], v[32:33], v[40:41] op_sel_hi:[1,0]
	v_pk_fma_f32 v[36:37], v[68:69], v[36:37], v[42:43]
	v_pk_fma_f32 v[38:39], v[70:71], v[38:39], v[44:45]
	v_pk_fma_f32 v[40:41], v[64:65], v[32:33], v[46:47]
	v_pk_fma_f32 v[42:43], v[66:67], v[34:35], v[48:49]
	v_cvt_pk_bf16_f32 v32, v36, v37
	v_cvt_pk_bf16_f32 v33, v38, v39
	v_cvt_pk_bf16_f32 v34, v40, v41
	v_lshlrev_b32_e32 v38, 16, v142
	v_cvt_pk_bf16_f32 v35, v42, v43
	global_store_dwordx4 v[96:97], v[32:35], off offset:256 sc1
	ds_read_b32 v32, v206 offset:8704
	v_and_b32_e32 v39, 0xffff0000, v142
	v_lshlrev_b32_e32 v34, 16, v140
	v_and_b32_e32 v35, 0xffff0000, v140
	v_lshlrev_b32_e32 v36, 16, v141
	s_waitcnt lgkmcnt(0)
	v_pk_mul_f32 v[28:29], v[28:29], v[32:33] op_sel_hi:[1,0]
	v_pk_mul_f32 v[24:25], v[24:25], v[32:33] op_sel_hi:[1,0]
	v_and_b32_e32 v37, 0xffff0000, v141
	v_lshlrev_b32_e32 v40, 16, v143
	v_and_b32_e32 v41, 0xffff0000, v143
	v_pk_mul_f32 v[30:31], v[30:31], v[32:33] op_sel_hi:[1,0]
	v_pk_fma_f32 v[28:29], v[68:69], v[28:29], v[34:35]
	v_pk_mul_f32 v[26:27], v[26:27], v[32:33] op_sel_hi:[1,0]
	v_pk_fma_f32 v[32:33], v[64:65], v[24:25], v[38:39]
	v_cvt_pk_bf16_f32 v24, v28, v29
	v_pk_fma_f32 v[30:31], v[70:71], v[30:31], v[36:37]
	v_pk_fma_f32 v[34:35], v[66:67], v[26:27], v[40:41]
	v_cvt_pk_bf16_f32 v25, v30, v31
	v_cvt_pk_bf16_f32 v26, v32, v33
	v_lshlrev_b32_e32 v28, 16, v137
	v_cvt_pk_bf16_f32 v27, v34, v35
	global_store_dwordx4 v[88:89], v[24:27], off offset:256 sc1
	ds_read_b32 v24, v206 offset:8768
	v_and_b32_e32 v29, 0xffff0000, v137
	v_lshlrev_b32_e32 v26, 16, v136
	v_and_b32_e32 v27, 0xffff0000, v136
	v_lshlrev_b32_e32 v30, 16, v138
	v_and_b32_e32 v31, 0xffff0000, v138
	v_lshlrev_b32_e32 v32, 16, v139
	v_and_b32_e32 v33, 0xffff0000, v139
	s_waitcnt lgkmcnt(0)
	v_pk_mul_f32 v[22:23], v[22:23], v[24:25] op_sel_hi:[1,0]
	v_pk_mul_f32 v[20:21], v[20:21], v[24:25] op_sel_hi:[1,0]
	v_pk_mul_f32 v[18:19], v[18:19], v[24:25] op_sel_hi:[1,0]
	v_pk_mul_f32 v[16:17], v[16:17], v[24:25] op_sel_hi:[1,0]
	v_pk_fma_f32 v[20:21], v[68:69], v[20:21], v[26:27]
	v_pk_fma_f32 v[22:23], v[70:71], v[22:23], v[28:29]
	v_pk_fma_f32 v[24:25], v[64:65], v[16:17], v[30:31]
	v_pk_fma_f32 v[26:27], v[66:67], v[18:19], v[32:33]
	v_cvt_pk_bf16_f32 v16, v20, v21
	v_cvt_pk_bf16_f32 v17, v22, v23
	v_cvt_pk_bf16_f32 v18, v24, v25
	v_lshlrev_b32_e32 v22, 16, v134
	v_cvt_pk_bf16_f32 v19, v26, v27
	global_store_dwordx4 v[80:81], v[16:19], off offset:256 sc1
	ds_read_b32 v16, v206 offset:8832
	v_and_b32_e32 v23, 0xffff0000, v134
	v_lshlrev_b32_e32 v18, 16, v132
	v_and_b32_e32 v19, 0xffff0000, v132
	v_lshlrev_b32_e32 v20, 16, v133
	s_waitcnt lgkmcnt(0)
	v_pk_mul_f32 v[12:13], v[12:13], v[16:17] op_sel_hi:[1,0]
	v_pk_mul_f32 v[8:9], v[8:9], v[16:17] op_sel_hi:[1,0]
	v_and_b32_e32 v21, 0xffff0000, v133
	v_lshlrev_b32_e32 v24, 16, v135
	v_and_b32_e32 v25, 0xffff0000, v135
	v_pk_mul_f32 v[14:15], v[14:15], v[16:17] op_sel_hi:[1,0]
	v_pk_fma_f32 v[12:13], v[68:69], v[12:13], v[18:19]
	v_pk_mul_f32 v[10:11], v[10:11], v[16:17] op_sel_hi:[1,0]
	v_pk_fma_f32 v[16:17], v[64:65], v[8:9], v[22:23]
	v_cvt_pk_bf16_f32 v8, v12, v13
	v_pk_fma_f32 v[14:15], v[70:71], v[14:15], v[20:21]
	v_pk_fma_f32 v[18:19], v[66:67], v[10:11], v[24:25]
	v_cvt_pk_bf16_f32 v9, v14, v15
	v_cvt_pk_bf16_f32 v10, v16, v17
	v_lshlrev_b32_e32 v12, 16, v129
	v_cvt_pk_bf16_f32 v11, v18, v19
	global_store_dwordx4 v[72:73], v[8:11], off offset:256 sc1
	ds_read_b32 v8, v206 offset:8896
	v_and_b32_e32 v13, 0xffff0000, v129
	v_lshlrev_b32_e32 v10, 16, v128
	v_and_b32_e32 v11, 0xffff0000, v128
	v_lshlrev_b32_e32 v14, 16, v130
	v_and_b32_e32 v15, 0xffff0000, v130
	v_lshlrev_b32_e32 v16, 16, v131
	v_and_b32_e32 v17, 0xffff0000, v131
	s_waitcnt lgkmcnt(0)
	v_pk_mul_f32 v[6:7], v[6:7], v[8:9] op_sel_hi:[1,0]
	v_pk_mul_f32 v[4:5], v[4:5], v[8:9] op_sel_hi:[1,0]
	v_pk_mul_f32 v[2:3], v[2:3], v[8:9] op_sel_hi:[1,0]
	v_pk_mul_f32 v[0:1], v[0:1], v[8:9] op_sel_hi:[1,0]
	v_pk_fma_f32 v[4:5], v[68:69], v[4:5], v[10:11]
	v_pk_fma_f32 v[6:7], v[70:71], v[6:7], v[12:13]
	v_pk_fma_f32 v[8:9], v[64:65], v[0:1], v[14:15]
	v_pk_fma_f32 v[10:11], v[66:67], v[2:3], v[16:17]
	v_cvt_pk_bf16_f32 v0, v4, v5
	v_cvt_pk_bf16_f32 v1, v6, v7
	v_cvt_pk_bf16_f32 v2, v8, v9
	s_nop 0
	v_cvt_pk_bf16_f32 v3, v10, v11
	global_store_dwordx4 v[74:75], v[0:3], off offset:256 sc1
